# P0 x->bf16 pass: four rows per trip with all loads in flight, DPP row sum
# speedup vs baseline: 1.0027x; 1.0027x over previous
.Lp0x_chk:
	s_mul_i32 s8, s82, 3
	s_add_i32 s8, s8, s70
	s_cmp_lt_i32 s8, 0x8000
	s_cbranch_scc0 .Lp0x_tail
	v_lshl_add_u64 v[128:129], v[6:7], 0, s[12:13]
	v_lshl_add_u64 v[130:131], v[128:129], 0, s[12:13]
	v_lshl_add_u64 v[132:133], v[130:131], 0, s[12:13]
	global_load_dwordx4 v[14:17], v[6:7], off offset:-3072 nt
	global_load_dwordx4 v[18:21], v[6:7], off offset:-2048 nt
	global_load_dwordx4 v[22:25], v[6:7], off offset:-1024 nt
	global_load_dwordx4 v[26:29], v[6:7], off nt
	global_load_dwordx4 v[136:139], v[128:129], off offset:-3072 nt
	global_load_dwordx4 v[140:143], v[128:129], off offset:-2048 nt
	global_load_dwordx4 v[144:147], v[128:129], off offset:-1024 nt
	global_load_dwordx4 v[148:151], v[128:129], off nt
	global_load_dwordx4 v[152:155], v[130:131], off offset:-3072 nt
	global_load_dwordx4 v[156:159], v[130:131], off offset:-2048 nt
	global_load_dwordx4 v[160:163], v[130:131], off offset:-1024 nt
	global_load_dwordx4 v[164:167], v[130:131], off nt
	global_load_dwordx4 v[168:171], v[132:133], off offset:-3072 nt
	global_load_dwordx4 v[172:175], v[132:133], off offset:-2048 nt
	global_load_dwordx4 v[176:179], v[132:133], off offset:-1024 nt
	global_load_dwordx4 v[180:183], v[132:133], off nt
	v_lshl_add_u64 v[6:7], v[132:133], 0, s[12:13]
	v_lshl_add_u64 v[188:189], s[30:31], 0, v[4:5]
	v_lshl_add_u64 v[196:197], s[30:31], 0, v[2:3]
	v_add_co_u32_e64 v188, s[8:9], s3, v188
	v_lshl_add_u64 v[4:5], v[4:5], 0, s[76:77]
	v_addc_co_u32_e64 v189, s[8:9], 0, v189, s[8:9]
	v_lshl_add_u64 v[2:3], v[2:3], 0, s[74:75]
	v_lshl_add_u64 v[190:191], s[30:31], 0, v[4:5]
	v_lshl_add_u64 v[198:199], s[30:31], 0, v[2:3]
	v_add_co_u32_e64 v190, s[8:9], s3, v190
	v_lshl_add_u64 v[4:5], v[4:5], 0, s[76:77]
	v_addc_co_u32_e64 v191, s[8:9], 0, v191, s[8:9]
	v_lshl_add_u64 v[2:3], v[2:3], 0, s[74:75]
	v_lshl_add_u64 v[192:193], s[30:31], 0, v[4:5]
	v_lshl_add_u64 v[200:201], s[30:31], 0, v[2:3]
	v_add_co_u32_e64 v192, s[8:9], s3, v192
	v_lshl_add_u64 v[4:5], v[4:5], 0, s[76:77]
	v_addc_co_u32_e64 v193, s[8:9], 0, v193, s[8:9]
	v_lshl_add_u64 v[2:3], v[2:3], 0, s[74:75]
	v_lshl_add_u64 v[194:195], s[30:31], 0, v[4:5]
	v_lshl_add_u64 v[202:203], s[30:31], 0, v[2:3]
	v_add_co_u32_e64 v194, s[8:9], s3, v194
	v_lshl_add_u64 v[4:5], v[4:5], 0, s[76:77]
	v_addc_co_u32_e64 v195, s[8:9], 0, v195, s[8:9]
	v_lshl_add_u64 v[2:3], v[2:3], 0, s[74:75]
	s_waitcnt vmcnt(12)
	v_mul_f32_e32 v184, v15, v15
	v_mul_f32_e32 v30, v17, v17
	v_mul_f32_e32 v31, v19, v19
	v_mul_f32_e32 v32, v21, v21
	v_mul_f32_e32 v33, v23, v23
	v_mul_f32_e32 v34, v25, v25
	v_fmac_f32_e32 v184, v14, v14
	v_fmac_f32_e32 v30, v16, v16
	v_fmac_f32_e32 v31, v18, v18
	v_fmac_f32_e32 v32, v20, v20
	v_mul_f32_e32 v35, v27, v27
	v_mul_f32_e32 v36, v29, v29
	v_fmac_f32_e32 v33, v22, v22
	v_fmac_f32_e32 v34, v24, v24
	v_add_f32_e32 v184, v184, v30
	v_add_f32_e32 v30, v31, v32
	v_fmac_f32_e32 v35, v26, v26
	v_fmac_f32_e32 v36, v28, v28
	v_add_f32_e32 v31, v33, v34
	v_add_f32_e32 v184, v184, v30
	v_add_f32_e32 v32, v35, v36
	v_add_f32_e32 v184, v184, v31
	v_add_f32_e32 v184, v184, v32
	v_cvt_pk_bf16_f32 v14, v14, v15
	v_cvt_pk_bf16_f32 v15, v16, v17
	v_add_f32_dpp v184, v184, v184 quad_perm:[1,0,3,2] row_mask:0xf bank_mask:0xf
	v_cvt_pk_bf16_f32 v16, v18, v19
	v_cvt_pk_bf16_f32 v17, v20, v21
	v_add_f32_dpp v184, v184, v184 quad_perm:[2,3,0,1] row_mask:0xf bank_mask:0xf
	v_cvt_pk_bf16_f32 v18, v22, v23
	v_cvt_pk_bf16_f32 v19, v24, v25
	v_add_f32_dpp v184, v184, v184 row_ror:4 row_mask:0xf bank_mask:0xf
	v_cvt_pk_bf16_f32 v20, v26, v27
	v_cvt_pk_bf16_f32 v21, v28, v29
	v_add_f32_dpp v184, v184, v184 row_ror:8 row_mask:0xf bank_mask:0xf
	s_nop 1
	v_add_f32_dpp v184, v184, v184 row_bcast:15 row_mask:0xa bank_mask:0xf
	s_nop 1
	v_add_f32_dpp v184, v184, v184 row_bcast:31 row_mask:0xc bank_mask:0xf
	s_nop 1
	v_readlane_b32 s98, v184, 63
	s_nop 0
	v_mov_b32_e32 v184, s98
	v_cndmask_b32_e64 v184, 0, v184, s[6:7]
	s_waitcnt vmcnt(8)
	v_mul_f32_e32 v185, v137, v137
	v_mul_f32_e32 v30, v139, v139
	v_mul_f32_e32 v31, v141, v141
	v_mul_f32_e32 v32, v143, v143
	v_mul_f32_e32 v33, v145, v145
	v_mul_f32_e32 v34, v147, v147
	v_fmac_f32_e32 v185, v136, v136
	v_fmac_f32_e32 v30, v138, v138
	v_fmac_f32_e32 v31, v140, v140
	v_fmac_f32_e32 v32, v142, v142
	v_mul_f32_e32 v35, v149, v149
	v_mul_f32_e32 v36, v151, v151
	v_fmac_f32_e32 v33, v144, v144
	v_fmac_f32_e32 v34, v146, v146
	v_add_f32_e32 v185, v185, v30
	v_add_f32_e32 v30, v31, v32
	v_fmac_f32_e32 v35, v148, v148
	v_fmac_f32_e32 v36, v150, v150
	v_add_f32_e32 v31, v33, v34
	v_add_f32_e32 v185, v185, v30
	v_add_f32_e32 v32, v35, v36
	v_add_f32_e32 v185, v185, v31
	v_add_f32_e32 v185, v185, v32
	v_cvt_pk_bf16_f32 v136, v136, v137
	v_cvt_pk_bf16_f32 v137, v138, v139
	v_add_f32_dpp v185, v185, v185 quad_perm:[1,0,3,2] row_mask:0xf bank_mask:0xf
	v_cvt_pk_bf16_f32 v138, v140, v141
	v_cvt_pk_bf16_f32 v139, v142, v143
	v_add_f32_dpp v185, v185, v185 quad_perm:[2,3,0,1] row_mask:0xf bank_mask:0xf
	v_cvt_pk_bf16_f32 v140, v144, v145
	v_cvt_pk_bf16_f32 v141, v146, v147
	v_add_f32_dpp v185, v185, v185 row_ror:4 row_mask:0xf bank_mask:0xf
	v_cvt_pk_bf16_f32 v142, v148, v149
	v_cvt_pk_bf16_f32 v143, v150, v151
	v_add_f32_dpp v185, v185, v185 row_ror:8 row_mask:0xf bank_mask:0xf
	s_nop 1
	v_add_f32_dpp v185, v185, v185 row_bcast:15 row_mask:0xa bank_mask:0xf
	s_nop 1
	v_add_f32_dpp v185, v185, v185 row_bcast:31 row_mask:0xc bank_mask:0xf
	s_nop 1
	v_readlane_b32 s98, v185, 63
	s_nop 0
	v_mov_b32_e32 v185, s98
	v_cndmask_b32_e64 v185, 0, v185, s[6:7]
	s_waitcnt vmcnt(4)
	v_mul_f32_e32 v186, v153, v153
	v_mul_f32_e32 v30, v155, v155
	v_mul_f32_e32 v31, v157, v157
	v_mul_f32_e32 v32, v159, v159
	v_mul_f32_e32 v33, v161, v161
	v_mul_f32_e32 v34, v163, v163
	v_fmac_f32_e32 v186, v152, v152
	v_fmac_f32_e32 v30, v154, v154
	v_fmac_f32_e32 v31, v156, v156
	v_fmac_f32_e32 v32, v158, v158
	v_mul_f32_e32 v35, v165, v165
	v_mul_f32_e32 v36, v167, v167
	v_fmac_f32_e32 v33, v160, v160
	v_fmac_f32_e32 v34, v162, v162
	v_add_f32_e32 v186, v186, v30
	v_add_f32_e32 v30, v31, v32
	v_fmac_f32_e32 v35, v164, v164
	v_fmac_f32_e32 v36, v166, v166
	v_add_f32_e32 v31, v33, v34
	v_add_f32_e32 v186, v186, v30
	v_add_f32_e32 v32, v35, v36
	v_add_f32_e32 v186, v186, v31
	v_add_f32_e32 v186, v186, v32
	v_cvt_pk_bf16_f32 v152, v152, v153
	v_cvt_pk_bf16_f32 v153, v154, v155
	v_add_f32_dpp v186, v186, v186 quad_perm:[1,0,3,2] row_mask:0xf bank_mask:0xf
	v_cvt_pk_bf16_f32 v154, v156, v157
	v_cvt_pk_bf16_f32 v155, v158, v159
	v_add_f32_dpp v186, v186, v186 quad_perm:[2,3,0,1] row_mask:0xf bank_mask:0xf
	v_cvt_pk_bf16_f32 v156, v160, v161
	v_cvt_pk_bf16_f32 v157, v162, v163
	v_add_f32_dpp v186, v186, v186 row_ror:4 row_mask:0xf bank_mask:0xf
	v_cvt_pk_bf16_f32 v158, v164, v165
	v_cvt_pk_bf16_f32 v159, v166, v167
	v_add_f32_dpp v186, v186, v186 row_ror:8 row_mask:0xf bank_mask:0xf
	s_nop 1
	v_add_f32_dpp v186, v186, v186 row_bcast:15 row_mask:0xa bank_mask:0xf
	s_nop 1
	v_add_f32_dpp v186, v186, v186 row_bcast:31 row_mask:0xc bank_mask:0xf
	s_nop 1
	v_readlane_b32 s98, v186, 63
	s_nop 0
	v_mov_b32_e32 v186, s98
	v_cndmask_b32_e64 v186, 0, v186, s[6:7]
	s_waitcnt vmcnt(0)
	v_mul_f32_e32 v187, v169, v169
	v_mul_f32_e32 v30, v171, v171
	v_mul_f32_e32 v31, v173, v173
	v_mul_f32_e32 v32, v175, v175
	v_mul_f32_e32 v33, v177, v177
	v_mul_f32_e32 v34, v179, v179
	v_fmac_f32_e32 v187, v168, v168
	v_fmac_f32_e32 v30, v170, v170
	v_fmac_f32_e32 v31, v172, v172
	v_fmac_f32_e32 v32, v174, v174
	v_mul_f32_e32 v35, v181, v181
	v_mul_f32_e32 v36, v183, v183
	v_fmac_f32_e32 v33, v176, v176
	v_fmac_f32_e32 v34, v178, v178
	v_add_f32_e32 v187, v187, v30
	v_add_f32_e32 v30, v31, v32
	v_fmac_f32_e32 v35, v180, v180
	v_fmac_f32_e32 v36, v182, v182
	v_add_f32_e32 v31, v33, v34
	v_add_f32_e32 v187, v187, v30
	v_add_f32_e32 v32, v35, v36
	v_add_f32_e32 v187, v187, v31
	v_add_f32_e32 v187, v187, v32
	v_cvt_pk_bf16_f32 v168, v168, v169
	v_cvt_pk_bf16_f32 v169, v170, v171
	v_add_f32_dpp v187, v187, v187 quad_perm:[1,0,3,2] row_mask:0xf bank_mask:0xf
	v_cvt_pk_bf16_f32 v170, v172, v173
	v_cvt_pk_bf16_f32 v171, v174, v175
	v_add_f32_dpp v187, v187, v187 quad_perm:[2,3,0,1] row_mask:0xf bank_mask:0xf
	v_cvt_pk_bf16_f32 v172, v176, v177
	v_cvt_pk_bf16_f32 v173, v178, v179
	v_add_f32_dpp v187, v187, v187 row_ror:4 row_mask:0xf bank_mask:0xf
	v_cvt_pk_bf16_f32 v174, v180, v181
	v_cvt_pk_bf16_f32 v175, v182, v183
	v_add_f32_dpp v187, v187, v187 row_ror:8 row_mask:0xf bank_mask:0xf
	s_nop 1
	v_add_f32_dpp v187, v187, v187 row_bcast:15 row_mask:0xa bank_mask:0xf
	s_nop 1
	v_add_f32_dpp v187, v187, v187 row_bcast:31 row_mask:0xc bank_mask:0xf
	s_nop 1
	v_readlane_b32 s98, v187, 63
	s_nop 0
	v_mov_b32_e32 v187, s98
	v_cndmask_b32_e64 v187, 0, v187, s[6:7]
	global_store_dwordx2 v[188:189], v[14:15], off
	global_store_dwordx2 v[188:189], v[16:17], off offset:512
	global_store_dwordx2 v[188:189], v[18:19], off offset:1024
	global_store_dwordx2 v[188:189], v[20:21], off offset:1536
	global_store_dwordx2 v[190:191], v[136:137], off
	global_store_dwordx2 v[190:191], v[138:139], off offset:512
	global_store_dwordx2 v[190:191], v[140:141], off offset:1024
	global_store_dwordx2 v[190:191], v[142:143], off offset:1536
	global_store_dwordx2 v[192:193], v[152:153], off
	global_store_dwordx2 v[192:193], v[154:155], off offset:512
	global_store_dwordx2 v[192:193], v[156:157], off offset:1024
	global_store_dwordx2 v[192:193], v[158:159], off offset:1536
	global_store_dwordx2 v[194:195], v[168:169], off
	global_store_dwordx2 v[194:195], v[170:171], off offset:512
	global_store_dwordx2 v[194:195], v[172:173], off offset:1024
	global_store_dwordx2 v[194:195], v[174:175], off offset:1536
	s_and_saveexec_b64 s[8:9], vcc
	global_store_dword v[196:197], v184, off
	global_store_dword v[198:199], v185, off
	global_store_dword v[200:201], v186, off
	global_store_dword v[202:203], v187, off
	s_or_b64 exec, exec, s[8:9]
	s_mul_i32 s8, s82, 4
	s_add_i32 s70, s70, s8
	s_branch .Lp0x_chk
.Lp0x_tail:
	s_cmp_lt_i32 s70, 0x8000
	s_cbranch_scc0 .LBB0_92
	s_branch .LBB0_90
